# phase C final combine: the 16 n_z loads of an item issued together before the in-place stores instead of a load/store/vmcnt(0) ladder
# baseline (speedup 1.0000x reference)
; DI unsigned pk2(float lo, float hi) { f32x2 v = {lo, hi}; bf16x2_t b = __builtin_convertvector(v, bf16x2_t); return __builtin_bit_cast(unsigned, b); }
; DI float bflo(unsigned u) { return __uint_as_float(u << 16); }
; DI float bfhi(unsigned u) { return __uint_as_float(u & 0xffff0000u); }
; template <bool LAST>
; DI void nsa_finish(u32x2* lo, f32x4 (&O)[4][4], float (&m)[4], float (&l)[4], const float (&gate)[4], const bf16_t* zp, bf16_t* yp, float minit) {
; #pragma unroll
;   for (int hh = 0; hh < 4; ++hh) {
;     float lt = l[hh]; lt += __shfl_xor(lt, 16); lt += __shfl_xor(lt, 32);
;     const float f = lt > 0.f ? gate[hh] / lt : 0.f;
; #pragma unroll
;     for (int dt = 0; dt < 4; ++dt) {
;       const u32x2 a = lo[(hh * 4 + dt) * 64];
;       const f32x4 v = (f32x4){bflo(a[0]), bfhi(a[0]), bflo(a[1]), bfhi(a[1])} + O[hh][dt] * f;
;       if (LAST) {
;         const u32x2 zz = *(const u32x2*)(zp + hh * 64 + dt * 16);
;         *(u32x2*)(yp + hh * 64 + dt * 16) = (u32x2){pk2(v[0] * bflo(zz[0]), v[1] * bfhi(zz[0])), pk2(v[2] * bflo(zz[1]), v[3] * bfhi(zz[1]))};
.LBB0_705:
	s_or_b64 exec, exec, s[42:43]
	v_lshlrev_b64 v[2:3], 10, v[162:163]
	v_lshl_add_u64 v[2:3], s[40:41], 0, v[2:3]
	s_lshl_b32 s36, s29, 9
	v_lshl_add_u64 v[2:3], v[2:3], 0, s[36:37]
	v_lshlrev_b32_e32 v0, 1, v158
	v_lshl_add_u64 v[12:13], v[2:3], 0, v[0:1]
	s_mov_b64 s[0:1], 0x13570000
	v_lshl_add_u64 v[8:9], v[12:13], 0, s[0:1]
	global_load_dwordx2 v[176:177], v[8:9], off
	global_load_dwordx2 v[178:179], v[8:9], off offset:32
	global_load_dwordx2 v[180:181], v[8:9], off offset:64
	global_load_dwordx2 v[182:183], v[8:9], off offset:96
	global_load_dwordx2 v[184:185], v[8:9], off offset:128
	global_load_dwordx2 v[186:187], v[8:9], off offset:160
	global_load_dwordx2 v[188:189], v[8:9], off offset:192
	global_load_dwordx2 v[190:191], v[8:9], off offset:224
	global_load_dwordx2 v[192:193], v[8:9], off offset:256
	global_load_dwordx2 v[194:195], v[8:9], off offset:288
	global_load_dwordx2 v[196:197], v[8:9], off offset:320
	global_load_dwordx2 v[198:199], v[8:9], off offset:352
	global_load_dwordx2 v[200:201], v[8:9], off offset:384
	global_load_dwordx2 v[116:117], v[8:9], off offset:416
	global_load_dwordx2 v[118:119], v[8:9], off offset:448
	global_load_dwordx2 v[120:121], v[8:9], off offset:480
	s_mov_b32 s0, 0x13570000
	v_add_co_u32_e32 v12, vcc, s0, v12
	v_addc_co_u32_e32 v13, vcc, 0, v13, vcc
	ds_bpermute_b32 v15, v175, v155
	ds_bpermute_b32 v14, v175, v154
	ds_read2st64_b64 v[20:23], v157 offset1:1
	s_add_i32 s27, s27, s94
	s_waitcnt lgkmcnt(1)
	v_pk_add_f32 v[14:15], v[154:155], v[14:15]
	ds_bpermute_b32 v109, v159, v15
	ds_bpermute_b32 v108, v159, v14
	s_waitcnt lgkmcnt(0)
	v_pk_add_f32 v[14:15], v[14:15], v[108:109]
	s_nop 0
	v_div_scale_f32 v0, s[0:1], v15, v15, v4
	v_rcp_f32_e32 v108, v0
	v_cmp_lt_f32_e64 s[0:1], 0, v14
	v_fma_f32 v109, -v0, v108, 1.0
	v_fmac_f32_e32 v108, v109, v108
	v_div_scale_f32 v109, vcc, v4, v15, v4
	v_mul_f32_e32 v110, v109, v108
	v_fma_f32 v111, -v0, v110, v109
	v_fmac_f32_e32 v110, v111, v108
	v_fma_f32 v0, -v0, v110, v109
	v_div_fmas_f32 v0, v0, v108, v110
	v_div_fixup_f32 v0, v0, v15, v4
	v_cmp_lt_f32_e32 vcc, 0, v15
	s_waitcnt vmcnt(0)
	v_mov_b64_e32 v[24:25], v[178:179]
	v_mov_b64_e32 v[34:35], v[180:181]
	v_mov_b64_e32 v[104:105], v[182:183]
	v_mov_b64_e32 v[16:17], v[176:177]
	v_lshlrev_b32_e32 v28, 16, v24
	v_and_b32_e32 v29, 0xffff0000, v24
	v_lshlrev_b32_e32 v30, 16, v25
	v_and_b32_e32 v31, 0xffff0000, v25
	ds_read2st64_b64 v[24:27], v157 offset0:2 offset1:3
	v_lshlrev_b32_e32 v2, 16, v20
	v_and_b32_e32 v3, 0xffff0000, v20
	v_lshlrev_b32_e32 v10, 16, v21
	v_and_b32_e32 v11, 0xffff0000, v21
	v_cndmask_b32_e32 v0, 0, v0, vcc
	v_lshlrev_b32_e32 v20, 16, v16
	v_and_b32_e32 v21, 0xffff0000, v16
	v_lshlrev_b32_e32 v18, 16, v17
	v_and_b32_e32 v19, 0xffff0000, v17
	v_pk_fma_f32 v[10:11], v[102:103], v[0:1], v[10:11] op_sel_hi:[1,0,1]
	v_pk_fma_f32 v[2:3], v[100:101], v[0:1], v[2:3] op_sel_hi:[1,0,1]
	v_pk_mul_f32 v[10:11], v[10:11], v[18:19]
	v_pk_mul_f32 v[2:3], v[2:3], v[20:21]
	v_lshlrev_b32_e32 v16, 16, v22
	v_cvt_pk_bf16_f32 v2, v2, v3
	v_cvt_pk_bf16_f32 v3, v10, v11
	global_store_dwordx2 v[12:13], v[2:3], off
	s_nop 1
	v_mov_b64_e32 v[12:13], v[184:185]
	v_and_b32_e32 v17, 0xffff0000, v22
	v_lshlrev_b32_e32 v22, 16, v23
	v_and_b32_e32 v23, 0xffff0000, v23
	v_pk_fma_f32 v[2:3], v[98:99], v[0:1], v[22:23] op_sel_hi:[1,0,1]
	v_pk_fma_f32 v[10:11], v[96:97], v[0:1], v[16:17] op_sel_hi:[1,0,1]
	v_pk_mul_f32 v[2:3], v[2:3], v[30:31]
	v_pk_mul_f32 v[10:11], v[10:11], v[28:29]
	s_waitcnt lgkmcnt(0)
	v_lshlrev_b32_e32 v32, 16, v24
	v_and_b32_e32 v33, 0xffff0000, v24
	v_lshlrev_b32_e32 v24, 16, v25
	v_and_b32_e32 v25, 0xffff0000, v25
	v_cvt_pk_bf16_f32 v10, v10, v11
	v_cvt_pk_bf16_f32 v11, v2, v3
	v_lshlrev_b32_e32 v36, 16, v34
	v_and_b32_e32 v37, 0xffff0000, v34
	v_lshlrev_b32_e32 v34, 16, v35
	v_and_b32_e32 v35, 0xffff0000, v35
	global_store_dwordx2 v[8:9], v[10:11], off offset:32
	v_pk_fma_f32 v[2:3], v[94:95], v[0:1], v[24:25] op_sel_hi:[1,0,1]
	v_pk_fma_f32 v[10:11], v[92:93], v[0:1], v[32:33] op_sel_hi:[1,0,1]
	v_pk_mul_f32 v[2:3], v[2:3], v[34:35]
	v_pk_mul_f32 v[10:11], v[10:11], v[36:37]
	v_lshlrev_b32_e32 v38, 16, v26
	v_and_b32_e32 v39, 0xffff0000, v26
	v_lshlrev_b32_e32 v26, 16, v27
	v_and_b32_e32 v27, 0xffff0000, v27
	v_cvt_pk_bf16_f32 v10, v10, v11
	v_cvt_pk_bf16_f32 v11, v2, v3
	v_lshlrev_b32_e32 v106, 16, v104
	v_and_b32_e32 v107, 0xffff0000, v104
	v_lshlrev_b32_e32 v104, 16, v105
	v_and_b32_e32 v105, 0xffff0000, v105
	global_store_dwordx2 v[8:9], v[10:11], off offset:64
	v_pk_fma_f32 v[2:3], v[90:91], v[0:1], v[26:27] op_sel_hi:[1,0,1]
	v_pk_fma_f32 v[10:11], v[88:89], v[0:1], v[38:39] op_sel_hi:[1,0,1]
	v_pk_mul_f32 v[2:3], v[2:3], v[104:105]
	v_pk_mul_f32 v[10:11], v[10:11], v[106:107]
	v_div_scale_f32 v0, s[8:9], v14, v14, v5
	v_cvt_pk_bf16_f32 v10, v10, v11
	v_cvt_pk_bf16_f32 v11, v2, v3
	v_rcp_f32_e32 v2, v0
	global_store_dwordx2 v[8:9], v[10:11], off offset:96
	s_nop 1
	v_mov_b64_e32 v[30:31], v[196:197]
	s_nop 1
	v_mov_b64_e32 v[36:37], v[198:199]
	v_fma_f32 v3, -v0, v2, 1.0
	v_fmac_f32_e32 v2, v3, v2
	v_div_scale_f32 v3, vcc, v5, v14, v5
	v_mul_f32_e32 v4, v3, v2
	v_fma_f32 v10, -v0, v4, v3
	v_fmac_f32_e32 v4, v10, v2
	v_fma_f32 v0, -v0, v4, v3
	v_div_fmas_f32 v0, v0, v2, v4
	v_div_fixup_f32 v0, v0, v14, v5
	ds_read2st64_b64 v[2:5], v157 offset0:4 offset1:5
	v_cndmask_b32_e64 v0, 0, v0, s[0:1]
	s_waitcnt lgkmcnt(0)
; DI unsigned pk2(float lo, float hi) { f32x2 v = {lo, hi}; bf16x2_t b = __builtin_convertvector(v, bf16x2_t); return __builtin_bit_cast(unsigned, b); }
; DI float bflo(unsigned u) { return __uint_as_float(u << 16); }
; DI float bfhi(unsigned u) { return __uint_as_float(u & 0xffff0000u); }
; template <bool LAST>
; DI void nsa_finish(u32x2* lo, f32x4 (&O)[4][4], float (&m)[4], float (&l)[4], const float (&gate)[4], const bf16_t* zp, bf16_t* yp, float minit) {
; #pragma unroll
;   for (int hh = 0; hh < 4; ++hh) {
;     float lt = l[hh]; lt += __shfl_xor(lt, 16); lt += __shfl_xor(lt, 32);
;     const float f = lt > 0.f ? gate[hh] / lt : 0.f;
; #pragma unroll
;     for (int dt = 0; dt < 4; ++dt) {
;       const u32x2 a = lo[(hh * 4 + dt) * 64];
;       const f32x4 v = (f32x4){bflo(a[0]), bfhi(a[0]), bflo(a[1]), bfhi(a[1])} + O[hh][dt] * f;
;       if (LAST) {
;         const u32x2 zz = *(const u32x2*)(zp + hh * 64 + dt * 16);
;         *(u32x2*)(yp + hh * 64 + dt * 16) = (u32x2){pk2(v[0] * bflo(zz[0]), v[1] * bfhi(zz[0])), pk2(v[2] * bflo(zz[1]), v[3] * bfhi(zz[1]))};
	v_lshlrev_b32_e32 v10, 16, v2
	v_and_b32_e32 v11, 0xffff0000, v2
	v_lshlrev_b32_e32 v2, 16, v3
	v_and_b32_e32 v3, 0xffff0000, v3
	v_pk_fma_f32 v[2:3], v[86:87], v[0:1], v[2:3] op_sel_hi:[1,0,1]
	v_pk_fma_f32 v[10:11], v[84:85], v[0:1], v[10:11] op_sel_hi:[1,0,1]
	v_lshlrev_b32_e32 v14, 16, v12
	v_and_b32_e32 v15, 0xffff0000, v12
	v_lshlrev_b32_e32 v12, 16, v13
	v_and_b32_e32 v13, 0xffff0000, v13
	v_pk_mul_f32 v[10:11], v[10:11], v[14:15]
	v_pk_mul_f32 v[2:3], v[2:3], v[12:13]
	v_cvt_pk_bf16_f32 v10, v10, v11
	v_cvt_pk_bf16_f32 v11, v2, v3
	global_store_dwordx2 v[8:9], v[10:11], off offset:128
	s_nop 1
	v_mov_b64_e32 v[10:11], v[186:187]
	v_lshlrev_b32_e32 v2, 16, v4
	v_and_b32_e32 v3, 0xffff0000, v4
	v_pk_fma_f32 v[2:3], v[80:81], v[0:1], v[2:3] op_sel_hi:[1,0,1]
	v_lshlrev_b32_e32 v4, 16, v5
	v_and_b32_e32 v5, 0xffff0000, v5
	v_pk_fma_f32 v[4:5], v[82:83], v[0:1], v[4:5] op_sel_hi:[1,0,1]
	v_lshlrev_b32_e32 v32, 16, v30
	v_and_b32_e32 v33, 0xffff0000, v30
	v_lshlrev_b32_e32 v30, 16, v31
	v_and_b32_e32 v31, 0xffff0000, v31
	v_lshlrev_b32_e32 v38, 16, v36
	v_and_b32_e32 v39, 0xffff0000, v36
	v_lshlrev_b32_e32 v36, 16, v37
	v_and_b32_e32 v37, 0xffff0000, v37
	v_lshlrev_b32_e32 v12, 16, v10
	v_and_b32_e32 v13, 0xffff0000, v10
	v_pk_mul_f32 v[2:3], v[2:3], v[12:13]
	s_nop 1
	v_mov_b64_e32 v[12:13], v[188:189]
	v_lshlrev_b32_e32 v10, 16, v11
	v_and_b32_e32 v11, 0xffff0000, v11
	v_pk_mul_f32 v[4:5], v[4:5], v[10:11]
	v_cvt_pk_bf16_f32 v2, v2, v3
	v_cvt_pk_bf16_f32 v3, v4, v5
	global_store_dwordx2 v[8:9], v[2:3], off offset:160
	ds_read2st64_b64 v[2:5], v157 offset0:6 offset1:7
	s_waitcnt lgkmcnt(0)
	v_lshlrev_b32_e32 v10, 16, v2
	v_and_b32_e32 v11, 0xffff0000, v2
	v_lshlrev_b32_e32 v2, 16, v3
	v_and_b32_e32 v3, 0xffff0000, v3
	v_pk_fma_f32 v[2:3], v[78:79], v[0:1], v[2:3] op_sel_hi:[1,0,1]
	v_pk_fma_f32 v[10:11], v[76:77], v[0:1], v[10:11] op_sel_hi:[1,0,1]
	v_lshlrev_b32_e32 v14, 16, v12
	v_and_b32_e32 v15, 0xffff0000, v12
	v_lshlrev_b32_e32 v12, 16, v13
	v_and_b32_e32 v13, 0xffff0000, v13
	v_pk_mul_f32 v[10:11], v[10:11], v[14:15]
	v_pk_mul_f32 v[2:3], v[2:3], v[12:13]
	v_cvt_pk_bf16_f32 v10, v10, v11
	v_cvt_pk_bf16_f32 v11, v2, v3
	global_store_dwordx2 v[8:9], v[10:11], off offset:192
	s_nop 1
	v_mov_b64_e32 v[10:11], v[190:191]
	v_lshlrev_b32_e32 v2, 16, v4
	v_and_b32_e32 v3, 0xffff0000, v4
	v_lshlrev_b32_e32 v4, 16, v5
	v_and_b32_e32 v5, 0xffff0000, v5
	v_pk_fma_f32 v[4:5], v[74:75], v[0:1], v[4:5] op_sel_hi:[1,0,1]
	v_pk_fma_f32 v[2:3], v[72:73], v[0:1], v[2:3] op_sel_hi:[1,0,1]
	v_lshlrev_b32_e32 v12, 16, v10
	v_and_b32_e32 v13, 0xffff0000, v10
	v_lshlrev_b32_e32 v10, 16, v11
	v_and_b32_e32 v11, 0xffff0000, v11
	v_pk_mul_f32 v[2:3], v[2:3], v[12:13]
	v_pk_mul_f32 v[4:5], v[4:5], v[10:11]
	v_cvt_pk_bf16_f32 v2, v2, v3
	v_cvt_pk_bf16_f32 v3, v4, v5
	global_store_dwordx2 v[8:9], v[2:3], off offset:224
	ds_read2st64_b64 v[2:5], v157 offset0:8 offset1:9
	ds_bpermute_b32 v11, v175, v153
	ds_bpermute_b32 v10, v175, v152
	s_waitcnt lgkmcnt(2)
	v_lshlrev_b32_e32 v12, 16, v2
	v_and_b32_e32 v13, 0xffff0000, v2
	v_lshlrev_b32_e32 v14, 16, v3
	v_and_b32_e32 v15, 0xffff0000, v3
	s_nop 1
	v_mov_b64_e32 v[2:3], v[192:193]
	s_waitcnt lgkmcnt(0)
	v_pk_add_f32 v[10:11], v[152:153], v[10:11]
	ds_bpermute_b32 v73, v159, v11
	ds_bpermute_b32 v72, v159, v10
	v_lshlrev_b32_e32 v20, 16, v4
	v_and_b32_e32 v21, 0xffff0000, v4
	v_lshlrev_b32_e32 v22, 16, v5
	v_and_b32_e32 v23, 0xffff0000, v5
	s_waitcnt lgkmcnt(0)
	v_pk_add_f32 v[10:11], v[10:11], v[72:73]
	v_lshlrev_b32_e32 v16, 16, v2
	v_and_b32_e32 v17, 0xffff0000, v2
	v_lshlrev_b32_e32 v18, 16, v3
	v_and_b32_e32 v19, 0xffff0000, v3
	s_nop 1
	v_mov_b64_e32 v[2:3], v[194:195]
	v_div_scale_f32 v0, s[0:1], v11, v11, v6
	v_rcp_f32_e32 v72, v0
	v_cmp_lt_f32_e64 s[0:1], 0, v10
	v_fma_f32 v73, -v0, v72, 1.0
	v_fmac_f32_e32 v72, v73, v72
	v_div_scale_f32 v73, vcc, v6, v11, v6
	v_mul_f32_e32 v74, v73, v72
	v_fma_f32 v75, -v0, v74, v73
	v_fmac_f32_e32 v74, v75, v72
	v_fma_f32 v0, -v0, v74, v73
	v_div_fmas_f32 v0, v0, v72, v74
	v_div_fixup_f32 v0, v0, v11, v6
	v_cmp_lt_f32_e32 vcc, 0, v11
	v_lshlrev_b32_e32 v24, 16, v2
	v_and_b32_e32 v25, 0xffff0000, v2
	v_lshlrev_b32_e32 v26, 16, v3
	v_and_b32_e32 v27, 0xffff0000, v3
	ds_read2st64_b64 v[2:5], v157 offset0:10 offset1:11
	v_cndmask_b32_e32 v0, 0, v0, vcc
	v_pk_fma_f32 v[14:15], v[70:71], v[0:1], v[14:15] op_sel_hi:[1,0,1]
	v_pk_fma_f32 v[12:13], v[68:69], v[0:1], v[12:13] op_sel_hi:[1,0,1]
	v_pk_mul_f32 v[14:15], v[14:15], v[18:19]
	v_pk_mul_f32 v[12:13], v[12:13], v[16:17]
	s_waitcnt lgkmcnt(0)
; DI unsigned pk2(float lo, float hi) { f32x2 v = {lo, hi}; bf16x2_t b = __builtin_convertvector(v, bf16x2_t); return __builtin_bit_cast(unsigned, b); }
; DI float bflo(unsigned u) { return __uint_as_float(u << 16); }
; DI float bfhi(unsigned u) { return __uint_as_float(u & 0xffff0000u); }
; template <bool LAST>
; DI void nsa_finish(u32x2* lo, f32x4 (&O)[4][4], float (&m)[4], float (&l)[4], const float (&gate)[4], const bf16_t* zp, bf16_t* yp, float minit) {
; #pragma unroll
;   for (int hh = 0; hh < 4; ++hh) {
;     float lt = l[hh]; lt += __shfl_xor(lt, 16); lt += __shfl_xor(lt, 32);
;     const float f = lt > 0.f ? gate[hh] / lt : 0.f;
; #pragma unroll
;     for (int dt = 0; dt < 4; ++dt) {
;       const u32x2 a = lo[(hh * 4 + dt) * 64];
;       const f32x4 v = (f32x4){bflo(a[0]), bfhi(a[0]), bflo(a[1]), bfhi(a[1])} + O[hh][dt] * f;
;       if (LAST) {
;         const u32x2 zz = *(const u32x2*)(zp + hh * 64 + dt * 16);
;         *(u32x2*)(yp + hh * 64 + dt * 16) = (u32x2){pk2(v[0] * bflo(zz[0]), v[1] * bfhi(zz[0])), pk2(v[2] * bflo(zz[1]), v[3] * bfhi(zz[1]))};
; DI void nsa_wave(const Params& p, int layer, int b, int g, int t0, unsigned char* lds, bf16_t* ybase) {
;     ...
;   __syncthreads();
; }
; DI void phaseC(const Params& p0, int layer, unsigned char* lds, bool probe) {
;   const int NITEM = BATCH * 2 * 16;
;   for (int it = blockIdx.x; it < NITEM; it += gridDim.x) {
	v_lshlrev_b32_e32 v28, 16, v2
	v_cvt_pk_bf16_f32 v12, v12, v13
	v_cvt_pk_bf16_f32 v13, v14, v15
	global_store_dwordx2 v[8:9], v[12:13], off offset:256
	v_pk_fma_f32 v[12:13], v[66:67], v[0:1], v[22:23] op_sel_hi:[1,0,1]
	v_pk_fma_f32 v[14:15], v[64:65], v[0:1], v[20:21] op_sel_hi:[1,0,1]
	v_and_b32_e32 v29, 0xffff0000, v2
	v_lshlrev_b32_e32 v2, 16, v3
	v_and_b32_e32 v3, 0xffff0000, v3
	v_pk_mul_f32 v[14:15], v[14:15], v[24:25]
	v_pk_mul_f32 v[12:13], v[12:13], v[26:27]
	v_cvt_pk_bf16_f32 v14, v14, v15
	v_cvt_pk_bf16_f32 v15, v12, v13
	v_pk_fma_f32 v[2:3], v[62:63], v[0:1], v[2:3] op_sel_hi:[1,0,1]
	v_pk_fma_f32 v[12:13], v[60:61], v[0:1], v[28:29] op_sel_hi:[1,0,1]
	v_lshlrev_b32_e32 v34, 16, v4
	v_and_b32_e32 v35, 0xffff0000, v4
	v_lshlrev_b32_e32 v4, 16, v5
	v_and_b32_e32 v5, 0xffff0000, v5
	v_pk_mul_f32 v[12:13], v[12:13], v[32:33]
	v_pk_mul_f32 v[2:3], v[2:3], v[30:31]
	v_cvt_pk_bf16_f32 v12, v12, v13
	v_cvt_pk_bf16_f32 v13, v2, v3
	v_pk_fma_f32 v[2:3], v[58:59], v[0:1], v[4:5] op_sel_hi:[1,0,1]
	v_pk_fma_f32 v[4:5], v[56:57], v[0:1], v[34:35] op_sel_hi:[1,0,1]
	v_pk_mul_f32 v[2:3], v[2:3], v[36:37]
	v_pk_mul_f32 v[4:5], v[4:5], v[38:39]
	v_div_scale_f32 v0, s[8:9], v10, v10, v7
	v_cvt_pk_bf16_f32 v4, v4, v5
	v_cvt_pk_bf16_f32 v5, v2, v3
	v_rcp_f32_e32 v2, v0
	global_store_dwordx2 v[8:9], v[4:5], off offset:352
	global_store_dwordx2 v[8:9], v[12:13], off offset:320
	global_store_dwordx2 v[8:9], v[14:15], off offset:288
	v_fma_f32 v3, -v0, v2, 1.0
	v_fmac_f32_e32 v2, v3, v2
	v_div_scale_f32 v3, vcc, v7, v10, v7
	v_mul_f32_e32 v4, v3, v2
	v_fma_f32 v5, -v0, v4, v3
	v_fmac_f32_e32 v4, v5, v2
	v_fma_f32 v0, -v0, v4, v3
	v_div_fmas_f32 v0, v0, v2, v4
	v_div_fixup_f32 v0, v0, v10, v7
	s_nop 1
	v_mov_b64_e32 v[10:11], v[200:201]
	ds_read2st64_b64 v[2:5], v157 offset0:12 offset1:13
	v_cndmask_b32_e64 v0, 0, v0, s[0:1]
	v_readlane_b32 s0, v254, 55
	v_readlane_b32 s1, v254, 56
	s_xor_b64 s[2:3], s[2:3], s[0:1]
	s_waitcnt lgkmcnt(0)
	v_lshlrev_b32_e32 v6, 16, v2
	v_and_b32_e32 v7, 0xffff0000, v2
	v_lshlrev_b32_e32 v2, 16, v3
	v_and_b32_e32 v3, 0xffff0000, v3
	v_pk_fma_f32 v[2:3], v[54:55], v[0:1], v[2:3] op_sel_hi:[1,0,1]
	v_pk_fma_f32 v[6:7], v[52:53], v[0:1], v[6:7] op_sel_hi:[1,0,1]
	s_cmpk_lt_i32 s27, 0x200
	v_lshlrev_b32_e32 v12, 16, v10
	v_and_b32_e32 v13, 0xffff0000, v10
	v_lshlrev_b32_e32 v10, 16, v11
	v_and_b32_e32 v11, 0xffff0000, v11
	v_pk_mul_f32 v[6:7], v[6:7], v[12:13]
	v_pk_mul_f32 v[2:3], v[2:3], v[10:11]
	v_cvt_pk_bf16_f32 v6, v6, v7
	v_cvt_pk_bf16_f32 v7, v2, v3
	global_store_dwordx2 v[8:9], v[6:7], off offset:384
	v_lshlrev_b32_e32 v6, 16, v4
	v_and_b32_e32 v7, 0xffff0000, v4
	v_lshlrev_b32_e32 v2, 16, v5
	v_and_b32_e32 v3, 0xffff0000, v5
	v_pk_fma_f32 v[4:5], v[48:49], v[0:1], v[6:7] op_sel_hi:[1,0,1]
	s_nop 1
	v_mov_b64_e32 v[6:7], v[116:117]
	v_pk_fma_f32 v[2:3], v[50:51], v[0:1], v[2:3] op_sel_hi:[1,0,1]
	v_lshlrev_b32_e32 v10, 16, v6
	v_and_b32_e32 v11, 0xffff0000, v6
	v_pk_mul_f32 v[4:5], v[4:5], v[10:11]
	s_nop 1
	v_mov_b64_e32 v[10:11], v[118:119]
	v_lshlrev_b32_e32 v6, 16, v7
	v_and_b32_e32 v7, 0xffff0000, v7
	v_pk_mul_f32 v[2:3], v[2:3], v[6:7]
	v_cvt_pk_bf16_f32 v4, v4, v5
	v_cvt_pk_bf16_f32 v5, v2, v3
	global_store_dwordx2 v[8:9], v[4:5], off offset:416
	ds_read2st64_b64 v[2:5], v157 offset0:14 offset1:15
	s_waitcnt lgkmcnt(0)
	v_lshlrev_b32_e32 v6, 16, v2
	v_and_b32_e32 v7, 0xffff0000, v2
	v_lshlrev_b32_e32 v2, 16, v3
	v_and_b32_e32 v3, 0xffff0000, v3
	v_pk_fma_f32 v[2:3], v[46:47], v[0:1], v[2:3] op_sel_hi:[1,0,1]
	v_pk_fma_f32 v[6:7], v[44:45], v[0:1], v[6:7] op_sel_hi:[1,0,1]
	v_lshlrev_b32_e32 v12, 16, v10
	v_and_b32_e32 v13, 0xffff0000, v10
	v_lshlrev_b32_e32 v10, 16, v11
	v_and_b32_e32 v11, 0xffff0000, v11
	v_pk_mul_f32 v[6:7], v[6:7], v[12:13]
	v_pk_mul_f32 v[2:3], v[2:3], v[10:11]
	v_cvt_pk_bf16_f32 v6, v6, v7
	v_cvt_pk_bf16_f32 v7, v2, v3
	global_store_dwordx2 v[8:9], v[6:7], off offset:448
	v_lshlrev_b32_e32 v6, 16, v4
	v_and_b32_e32 v7, 0xffff0000, v4
	v_lshlrev_b32_e32 v2, 16, v5
	v_and_b32_e32 v3, 0xffff0000, v5
	v_pk_fma_f32 v[4:5], v[40:41], v[0:1], v[6:7] op_sel_hi:[1,0,1]
	s_nop 1
	v_mov_b64_e32 v[6:7], v[120:121]
	v_pk_fma_f32 v[2:3], v[42:43], v[0:1], v[2:3] op_sel_hi:[1,0,1]
	v_lshlrev_b32_e32 v10, 16, v6
	v_and_b32_e32 v11, 0xffff0000, v6
	v_lshlrev_b32_e32 v6, 16, v7
	v_and_b32_e32 v7, 0xffff0000, v7
	v_pk_mul_f32 v[4:5], v[4:5], v[10:11]
	v_pk_mul_f32 v[2:3], v[2:3], v[6:7]
	v_cvt_pk_bf16_f32 v4, v4, v5
	v_cvt_pk_bf16_f32 v5, v2, v3
	global_store_dwordx2 v[8:9], v[4:5], off offset:480
	s_barrier
	s_cbranch_scc0 .LBB0_776
